# in-proj GEMM K-loop: LDS-DMA loads use scalar-base + 32-bit lane offset addressing instead of per-load 64-bit vector address adds
# speedup vs baseline: 1.0072x; 1.0072x over previous
; #define PG8_STAGE(bufoff, gbase, voff) do { _Pragma("unroll") for (int _i = 0; _i < 2; ++_i) \
;         __builtin_amdgcn_global_load_lds((const unsigned*)((const char*)(gbase) + (voff)[_i]), (PG8_LAS unsigned*)(lds + (bufoff) + ldsw + _i * 8192), 16, 0, 0); } while (0)
; #define PG8_LDA(dst, b, h) do { _Pragma("unroll") for (int m = 0; m < 4; ++m) _Pragma("unroll") for (int k = 0; k < 2; ++k) dst[m][k] = *(const PG8_LAS bf16x8*)(lds + PG8_SA(b, h) + aoff + m * 2048 + k * 1024); } while (0)
; #define PG8_LDB(dst, b, h) do { _Pragma("unroll") for (int n = 0; n < 2; ++n) _Pragma("unroll") for (int k = 0; k < 2; ++k) dst[n][k] = *(const PG8_LAS bf16x8*)(lds + PG8_SB(b, h) + boff + n * 2048 + k * 1024); } while (0)
; #define PG8_MMA(ai, bj, At, Bt) do { __builtin_amdgcn_s_setprio(1); _Pragma("unroll") for (int m = 0; m < 4; ++m) _Pragma("unroll") for (int n = 0; n < 2; ++n) _Pragma("unroll") for (int k = 0; k < 2; ++k) \
;         acc[ai][bj][m][n] = __builtin_amdgcn_mfma_f32_16x16x32_bf16(Bt[n][k], At[m][k], acc[ai][bj][m][n], 0, 0, 0); __builtin_amdgcn_s_setprio(0); } while (0)
; #define PG8_WAIT_V(n) asm volatile("s_waitcnt vmcnt(" #n ")" ::: "memory")
; #define PG8_WAIT_L(n) asm volatile("s_waitcnt lgkmcnt(" #n ")" ::: "memory")
; #define PG8_BAR __builtin_amdgcn_s_barrier()
; #define PG8_SCHED __builtin_amdgcn_sched_barrier(0)
; template <class Epi, class Sched, bool ALIGN_EPI = false, bool SP2 = false>
; __device__ __forceinline__ void gemm_phase(PG8_LAS unsigned char* lds, const Gemm g, const Sched& S, const Epi& E) {
;     ...
;             PG8_LDB(B0, 0, 0); PG8_LDB(B1, 0, 1); PG8_SCHED; PG8_LDA(At, 0, 0); PG8_STAGE(PG8_SA(1, 1), a1 + hstep, voffA);
;             PG8_WAIT_V(8); PG8_WAIT_L(0); PG8_BAR; PG8_MMA(0, 0, At, B0); PG8_MMA(0, 1, At, B1); PG8_BAR; PG8_SCHED;
;             PG8_LDA(At, 0, 1); PG8_STAGE(PG8_SB(0, 0), b2, voffB); PG8_STAGE(PG8_SB(0, 1), b2 + hstep, voffB); PG8_STAGE(PG8_SA(0, 0), a2, voffA);
;             PG8_WAIT_V(8); PG8_WAIT_L(0); PG8_BAR; PG8_MMA(1, 0, At, B0); PG8_MMA(1, 1, At, B1); PG8_BAR; PG8_SCHED;
.LBB0_123:
	s_add_u32 s8, s6, 0xfff80080
	s_addc_u32 s9, s7, -1
	s_add_i32 s43, 0, 0x10000
	s_cmp_eq_u32 s42, 28
	s_cselect_b32 s23, s15, s9
	s_cselect_b32 s22, s24, s8
	s_cselect_b32 s9, s17, s41
	s_cselect_b32 s8, s25, s40
	s_add_i32 s48, 0, 0x14000
	v_add_u32_e32 v172, s43, v165
	v_add_u32_e32 v188, s48, v165
	ds_read_b128 v[156:159], v172
	ds_read_b128 v[160:163], v172 offset:1024
	ds_read_b128 v[168:171], v172 offset:2048
	ds_read_b128 v[172:175], v172 offset:3072
	ds_read_b128 v[176:179], v188
	ds_read_b128 v[180:183], v188 offset:1024
	ds_read_b128 v[184:187], v188 offset:2048
	ds_read_b128 v[188:191], v188 offset:3072
	s_add_i32 m0, s31, 0xc000
	ds_read_b128 v[192:195], v167
	ds_read_b128 v[196:199], v167 offset:1024
	ds_read_b128 v[200:203], v167 offset:2048
	ds_read_b128 v[204:207], v167 offset:3072
	ds_read_b128 v[208:211], v167 offset:4096
	ds_read_b128 v[212:215], v167 offset:5120
	ds_read_b128 v[216:219], v167 offset:6144
	ds_read_b128 v[224:227], v167 offset:7168
	global_load_lds_dwordx4 v152, s[6:7]
	s_add_i32 m0, s31, 0xe000
	s_nop 0
	global_load_lds_dwordx4 v154, s[6:7]
	s_waitcnt vmcnt(8) lgkmcnt(0)
	s_barrier
	v_mfma_f32_16x16x32_bf16 v[144:147], v[156:159], v[192:195], v[144:147]
	v_mfma_f32_16x16x32_bf16 v[122:125], v[168:171], v[192:195], v[122:125]
	v_mfma_f32_16x16x32_bf16 v[110:113], v[156:159], v[200:203], v[110:113]
	v_mfma_f32_16x16x32_bf16 v[106:109], v[168:171], v[200:203], v[106:109]
	v_mfma_f32_16x16x32_bf16 v[94:97], v[156:159], v[208:211], v[94:97]
	v_mfma_f32_16x16x32_bf16 v[90:93], v[168:171], v[208:211], v[90:93]
	v_mfma_f32_16x16x32_bf16 v[78:81], v[156:159], v[216:219], v[78:81]
	v_mfma_f32_16x16x32_bf16 v[74:77], v[168:171], v[216:219], v[74:77]
	v_mfma_f32_16x16x32_bf16 v[144:147], v[160:163], v[196:199], v[144:147]
	v_mfma_f32_16x16x32_bf16 v[122:125], v[172:175], v[196:199], v[122:125]
	v_mfma_f32_16x16x32_bf16 v[110:113], v[160:163], v[204:207], v[110:113]
	v_mfma_f32_16x16x32_bf16 v[106:109], v[172:175], v[204:207], v[106:109]
	v_mfma_f32_16x16x32_bf16 v[94:97], v[160:163], v[212:215], v[94:97]
	v_mfma_f32_16x16x32_bf16 v[90:93], v[172:175], v[212:215], v[90:93]
	v_mfma_f32_16x16x32_bf16 v[78:81], v[160:163], v[224:227], v[78:81]
	v_mfma_f32_16x16x32_bf16 v[74:77], v[172:175], v[224:227], v[74:77]
	v_mfma_f32_16x16x32_bf16 v[118:121], v[176:179], v[192:195], v[118:121]
	v_mfma_f32_16x16x32_bf16 v[114:117], v[184:187], v[192:195], v[114:117]
	v_mfma_f32_16x16x32_bf16 v[102:105], v[176:179], v[200:203], v[102:105]
	v_mfma_f32_16x16x32_bf16 v[98:101], v[184:187], v[200:203], v[98:101]
	v_mfma_f32_16x16x32_bf16 v[86:89], v[176:179], v[208:211], v[86:89]
	v_mfma_f32_16x16x32_bf16 v[82:85], v[184:187], v[208:211], v[82:85]
	v_mfma_f32_16x16x32_bf16 v[70:73], v[176:179], v[216:219], v[70:73]
	v_mfma_f32_16x16x32_bf16 v[66:69], v[184:187], v[216:219], v[66:69]
	v_mfma_f32_16x16x32_bf16 v[118:121], v[180:183], v[196:199], v[118:121]
	v_mfma_f32_16x16x32_bf16 v[114:117], v[188:191], v[196:199], v[114:117]
	v_mfma_f32_16x16x32_bf16 v[102:105], v[180:183], v[204:207], v[102:105]
	v_mfma_f32_16x16x32_bf16 v[98:101], v[188:191], v[204:207], v[98:101]
	v_mfma_f32_16x16x32_bf16 v[86:89], v[180:183], v[212:215], v[86:89]
	v_mfma_f32_16x16x32_bf16 v[82:85], v[188:191], v[212:215], v[82:85]
	v_mfma_f32_16x16x32_bf16 v[70:73], v[180:183], v[224:227], v[70:73]
	v_mfma_f32_16x16x32_bf16 v[66:69], v[188:191], v[224:227], v[66:69]
	s_barrier
	s_add_i32 s43, s43, s30
	s_mov_b32 m0, s43
	ds_read_b128 v[192:195], v167 offset:16384
	ds_read_b128 v[196:199], v167 offset:17408
	ds_read_b128 v[200:203], v167 offset:18432
	ds_read_b128 v[204:207], v167 offset:19456
	ds_read_b128 v[208:211], v167 offset:20480
	ds_read_b128 v[212:215], v167 offset:21504
	ds_read_b128 v[216:219], v167 offset:22528
	ds_read_b128 v[224:227], v167 offset:23552
	global_load_lds_dwordx4 v0, s[8:9]
	s_add_i32 m0, s43, 0x2000
	s_add_u32 s82, s8, 0x80000
	s_addc_u32 s83, s9, 0
	s_add_i32 s43, s48, s30
	global_load_lds_dwordx4 v126, s[8:9]
	s_mov_b32 m0, s43
	v_lshl_add_u64 v[244:245], s[22:23], 0, v[148:149]
	global_load_lds_dwordx4 v0, s[82:83]
	s_add_i32 m0, s43, 0x2000
	s_nop 0
	global_load_lds_dwordx4 v126, s[82:83]
	s_mov_b32 m0, s31
	v_lshl_add_u64 v[232:233], s[22:23], 0, v[150:151]
	global_load_lds_dwordx4 v[232:233], off
	s_mov_b32 m0, s34
	s_nop 0
	global_load_lds_dwordx4 v[244:245], off
	s_waitcnt vmcnt(8) lgkmcnt(0)
	s_barrier
	v_mfma_f32_16x16x32_bf16 v[62:65], v[156:159], v[192:195], v[62:65]
	v_mfma_f32_16x16x32_bf16 v[58:61], v[168:171], v[192:195], v[58:61]
	v_mfma_f32_16x16x32_bf16 v[46:49], v[156:159], v[200:203], v[46:49]
	v_mfma_f32_16x16x32_bf16 v[42:45], v[168:171], v[200:203], v[42:45]
	v_mfma_f32_16x16x32_bf16 v[30:33], v[156:159], v[208:211], v[30:33]
	v_mfma_f32_16x16x32_bf16 v[26:29], v[168:171], v[208:211], v[26:29]
	v_mfma_f32_16x16x32_bf16 v[14:17], v[156:159], v[216:219], v[14:17]
	v_mfma_f32_16x16x32_bf16 v[10:13], v[168:171], v[216:219], v[10:13]
	v_mfma_f32_16x16x32_bf16 v[62:65], v[160:163], v[196:199], v[62:65]
	v_mfma_f32_16x16x32_bf16 v[58:61], v[172:175], v[196:199], v[58:61]
	v_mfma_f32_16x16x32_bf16 v[46:49], v[160:163], v[204:207], v[46:49]
	v_mfma_f32_16x16x32_bf16 v[42:45], v[172:175], v[204:207], v[42:45]
	v_mfma_f32_16x16x32_bf16 v[30:33], v[160:163], v[212:215], v[30:33]
	v_mfma_f32_16x16x32_bf16 v[26:29], v[172:175], v[212:215], v[26:29]
	v_mfma_f32_16x16x32_bf16 v[14:17], v[160:163], v[224:227], v[14:17]
	v_mfma_f32_16x16x32_bf16 v[10:13], v[172:175], v[224:227], v[10:13]
	v_mfma_f32_16x16x32_bf16 v[54:57], v[176:179], v[192:195], v[54:57]
	v_mfma_f32_16x16x32_bf16 v[50:53], v[184:187], v[192:195], v[50:53]
	v_mfma_f32_16x16x32_bf16 v[38:41], v[176:179], v[200:203], v[38:41]
	v_mfma_f32_16x16x32_bf16 v[34:37], v[184:187], v[200:203], v[34:37]
	v_mfma_f32_16x16x32_bf16 v[22:25], v[176:179], v[208:211], v[22:25]
	v_mfma_f32_16x16x32_bf16 v[18:21], v[184:187], v[208:211], v[18:21]
	v_mfma_f32_16x16x32_bf16 v[6:9], v[176:179], v[216:219], v[6:9]
	v_mfma_f32_16x16x32_bf16 v[2:5], v[184:187], v[216:219], v[2:5]
	v_mfma_f32_16x16x32_bf16 v[54:57], v[180:183], v[196:199], v[54:57]
	v_mfma_f32_16x16x32_bf16 v[50:53], v[188:191], v[196:199], v[50:53]
	v_mfma_f32_16x16x32_bf16 v[38:41], v[180:183], v[204:207], v[38:41]
	v_mfma_f32_16x16x32_bf16 v[34:37], v[188:191], v[204:207], v[34:37]
	v_mfma_f32_16x16x32_bf16 v[22:25], v[180:183], v[212:215], v[22:25]
	v_mfma_f32_16x16x32_bf16 v[18:21], v[188:191], v[212:215], v[18:21]
	v_mfma_f32_16x16x32_bf16 v[6:9], v[180:183], v[224:227], v[6:9]
	v_mfma_f32_16x16x32_bf16 v[2:5], v[188:191], v[224:227], v[2:5]
	s_barrier
; #define PG8_STAGE(bufoff, gbase, voff) do { _Pragma("unroll") for (int _i = 0; _i < 2; ++_i) \
;         __builtin_amdgcn_global_load_lds((const unsigned*)((const char*)(gbase) + (voff)[_i]), (PG8_LAS unsigned*)(lds + (bufoff) + ldsw + _i * 8192), 16, 0, 0); } while (0)
; #define PG8_LDA(dst, b, h) do { _Pragma("unroll") for (int m = 0; m < 4; ++m) _Pragma("unroll") for (int k = 0; k < 2; ++k) dst[m][k] = *(const PG8_LAS bf16x8*)(lds + PG8_SA(b, h) + aoff + m * 2048 + k * 1024); } while (0)
; #define PG8_LDB(dst, b, h) do { _Pragma("unroll") for (int n = 0; n < 2; ++n) _Pragma("unroll") for (int k = 0; k < 2; ++k) dst[n][k] = *(const PG8_LAS bf16x8*)(lds + PG8_SB(b, h) + boff + n * 2048 + k * 1024); } while (0)
; #define PG8_MMA(ai, bj, At, Bt) do { __builtin_amdgcn_s_setprio(1); _Pragma("unroll") for (int m = 0; m < 4; ++m) _Pragma("unroll") for (int n = 0; n < 2; ++n) _Pragma("unroll") for (int k = 0; k < 2; ++k) \
;         acc[ai][bj][m][n] = __builtin_amdgcn_mfma_f32_16x16x32_bf16(Bt[n][k], At[m][k], acc[ai][bj][m][n], 0, 0, 0); __builtin_amdgcn_s_setprio(0); } while (0)
; #define PG8_WAIT_V(n) asm volatile("s_waitcnt vmcnt(" #n ")" ::: "memory")
; #define PG8_WAIT_L(n) asm volatile("s_waitcnt lgkmcnt(" #n ")" ::: "memory")
; #define PG8_BAR __builtin_amdgcn_s_barrier()
; #define PG8_SCHED __builtin_amdgcn_sched_barrier(0)
; template <class Epi, class Sched, bool ALIGN_EPI = false, bool SP2 = false>
; __device__ __forceinline__ void gemm_phase(PG8_LAS unsigned char* lds, const Gemm g, const Sched& S, const Epi& E) {
;     ...
;         for (int t = 0; t < nt; t += 2) {
;     ...
;             PG8_LDB(B0, 1, 0); PG8_LDB(B1, 1, 1); PG8_SCHED; PG8_LDA(At, 1, 0); PG8_STAGE(PG8_SA(0, 1), a2 + hstep, voffA);
;             PG8_WAIT_V(8); PG8_WAIT_L(0); PG8_BAR; PG8_MMA(0, 0, At, B0); PG8_MMA(0, 1, At, B1); PG8_BAR; PG8_SCHED;
;             PG8_LDA(At, 1, 1); PG8_STAGE(PG8_SB(1, 0), b3, voffB); PG8_STAGE(PG8_SB(1, 1), b3 + hstep, voffB); PG8_STAGE(PG8_SA(1, 0), a3, voffA);
;             PG8_WAIT_V(8); PG8_WAIT_L(0); PG8_BAR; PG8_MMA(1, 0, At, B0); PG8_MMA(1, 1, At, B1); PG8_BAR; PG8_SCHED;
	s_add_i32 s43, 0, 0x18000
	s_add_i32 s48, 0, 0x1c000
	v_add_u32_e32 v172, s43, v165
	v_add_u32_e32 v188, s48, v165
	ds_read_b128 v[156:159], v172
	ds_read_b128 v[160:163], v172 offset:1024
	ds_read_b128 v[168:171], v172 offset:2048
	ds_read_b128 v[172:175], v172 offset:3072
	ds_read_b128 v[176:179], v188
	ds_read_b128 v[180:183], v188 offset:1024
	ds_read_b128 v[184:187], v188 offset:2048
	ds_read_b128 v[188:191], v188 offset:3072
	s_add_u32 s22, s22, 0x80000
	s_addc_u32 s23, s23, 0
	s_mov_b32 m0, s35
	ds_read_b128 v[192:195], v167 offset:32768
	ds_read_b128 v[196:199], v167 offset:33792
	ds_read_b128 v[200:203], v167 offset:34816
	ds_read_b128 v[204:207], v167 offset:35840
	ds_read_b128 v[208:211], v167 offset:36864
	ds_read_b128 v[212:215], v167 offset:37888
	ds_read_b128 v[216:219], v167 offset:38912
	ds_read_b128 v[224:227], v167 offset:39936
	global_load_lds_dwordx4 v150, s[22:23]
	s_mov_b32 m0, s36
	s_nop 0
	global_load_lds_dwordx4 v148, s[22:23]
	s_waitcnt vmcnt(8) lgkmcnt(0)
	s_barrier
	v_mfma_f32_16x16x32_bf16 v[144:147], v[156:159], v[192:195], v[144:147]
	v_mfma_f32_16x16x32_bf16 v[122:125], v[168:171], v[192:195], v[122:125]
	v_mfma_f32_16x16x32_bf16 v[110:113], v[156:159], v[200:203], v[110:113]
	v_mfma_f32_16x16x32_bf16 v[106:109], v[168:171], v[200:203], v[106:109]
	v_mfma_f32_16x16x32_bf16 v[94:97], v[156:159], v[208:211], v[94:97]
	v_mfma_f32_16x16x32_bf16 v[90:93], v[168:171], v[208:211], v[90:93]
	v_mfma_f32_16x16x32_bf16 v[78:81], v[156:159], v[216:219], v[78:81]
	v_mfma_f32_16x16x32_bf16 v[74:77], v[168:171], v[216:219], v[74:77]
	v_mfma_f32_16x16x32_bf16 v[144:147], v[160:163], v[196:199], v[144:147]
	v_mfma_f32_16x16x32_bf16 v[122:125], v[172:175], v[196:199], v[122:125]
	v_mfma_f32_16x16x32_bf16 v[110:113], v[160:163], v[204:207], v[110:113]
	v_mfma_f32_16x16x32_bf16 v[106:109], v[172:175], v[204:207], v[106:109]
	v_mfma_f32_16x16x32_bf16 v[94:97], v[160:163], v[212:215], v[94:97]
	v_mfma_f32_16x16x32_bf16 v[90:93], v[172:175], v[212:215], v[90:93]
	v_mfma_f32_16x16x32_bf16 v[78:81], v[160:163], v[224:227], v[78:81]
	v_mfma_f32_16x16x32_bf16 v[74:77], v[172:175], v[224:227], v[74:77]
	v_mfma_f32_16x16x32_bf16 v[118:121], v[176:179], v[192:195], v[118:121]
	v_mfma_f32_16x16x32_bf16 v[114:117], v[184:187], v[192:195], v[114:117]
	v_mfma_f32_16x16x32_bf16 v[102:105], v[176:179], v[200:203], v[102:105]
	v_mfma_f32_16x16x32_bf16 v[98:101], v[184:187], v[200:203], v[98:101]
	v_mfma_f32_16x16x32_bf16 v[86:89], v[176:179], v[208:211], v[86:89]
	v_mfma_f32_16x16x32_bf16 v[82:85], v[184:187], v[208:211], v[82:85]
	v_mfma_f32_16x16x32_bf16 v[70:73], v[176:179], v[216:219], v[70:73]
	v_mfma_f32_16x16x32_bf16 v[66:69], v[184:187], v[216:219], v[66:69]
	v_mfma_f32_16x16x32_bf16 v[118:121], v[180:183], v[196:199], v[118:121]
	v_mfma_f32_16x16x32_bf16 v[114:117], v[188:191], v[196:199], v[114:117]
	v_mfma_f32_16x16x32_bf16 v[102:105], v[180:183], v[204:207], v[102:105]
	v_mfma_f32_16x16x32_bf16 v[98:101], v[188:191], v[204:207], v[98:101]
	v_mfma_f32_16x16x32_bf16 v[86:89], v[180:183], v[212:215], v[86:89]
	v_mfma_f32_16x16x32_bf16 v[82:85], v[188:191], v[212:215], v[82:85]
	v_mfma_f32_16x16x32_bf16 v[70:73], v[180:183], v[224:227], v[70:73]
	v_mfma_f32_16x16x32_bf16 v[66:69], v[188:191], v[224:227], v[66:69]
	s_barrier
	s_add_i32 s22, s43, s30
	s_add_u32 s82, s8, s64
	s_addc_u32 s83, s9, s65
	s_mov_b32 m0, s22
	ds_read_b128 v[192:195], v167 offset:49152
	ds_read_b128 v[196:199], v167 offset:50176
	ds_read_b128 v[200:203], v167 offset:51200
	ds_read_b128 v[204:207], v167 offset:52224
	ds_read_b128 v[208:211], v167 offset:53248
	ds_read_b128 v[212:215], v167 offset:54272
	ds_read_b128 v[216:219], v167 offset:55296
	ds_read_b128 v[224:227], v167 offset:56320
	global_load_lds_dwordx4 v0, s[82:83]
	s_add_i32 m0, s22, 0x2000
	s_add_u32 s8, s8, 0x80080
	s_addc_u32 s9, s9, 0
	s_add_i32 s22, s48, s30
	global_load_lds_dwordx4 v126, s[82:83]
	s_mov_b32 m0, s22
	s_nop 0
	global_load_lds_dwordx4 v0, s[8:9]
	s_add_i32 m0, s22, 0x2000
	s_nop 0
	global_load_lds_dwordx4 v126, s[8:9]
	s_mov_b32 m0, s37
	v_lshl_add_u64 v[228:229], v[232:233], 0, s[64:65]
	global_load_lds_dwordx4 v[228:229], off
	s_mov_b32 m0, s76
	v_lshl_add_u64 v[228:229], v[244:245], 0, s[64:65]
	global_load_lds_dwordx4 v[228:229], off
	s_waitcnt vmcnt(8) lgkmcnt(0)
	s_barrier
	v_mfma_f32_16x16x32_bf16 v[62:65], v[156:159], v[192:195], v[62:65]
	v_mfma_f32_16x16x32_bf16 v[58:61], v[168:171], v[192:195], v[58:61]
	v_mfma_f32_16x16x32_bf16 v[46:49], v[156:159], v[200:203], v[46:49]
	v_mfma_f32_16x16x32_bf16 v[42:45], v[168:171], v[200:203], v[42:45]
	v_mfma_f32_16x16x32_bf16 v[30:33], v[156:159], v[208:211], v[30:33]
	v_mfma_f32_16x16x32_bf16 v[26:29], v[168:171], v[208:211], v[26:29]
	v_mfma_f32_16x16x32_bf16 v[14:17], v[156:159], v[216:219], v[14:17]
	v_mfma_f32_16x16x32_bf16 v[10:13], v[168:171], v[216:219], v[10:13]
	v_mfma_f32_16x16x32_bf16 v[62:65], v[160:163], v[196:199], v[62:65]
	v_mfma_f32_16x16x32_bf16 v[58:61], v[172:175], v[196:199], v[58:61]
	v_mfma_f32_16x16x32_bf16 v[46:49], v[160:163], v[204:207], v[46:49]
	v_mfma_f32_16x16x32_bf16 v[42:45], v[172:175], v[204:207], v[42:45]
	v_mfma_f32_16x16x32_bf16 v[30:33], v[160:163], v[212:215], v[30:33]
	v_mfma_f32_16x16x32_bf16 v[26:29], v[172:175], v[212:215], v[26:29]
	v_mfma_f32_16x16x32_bf16 v[14:17], v[160:163], v[224:227], v[14:17]
	v_mfma_f32_16x16x32_bf16 v[10:13], v[172:175], v[224:227], v[10:13]
	v_mfma_f32_16x16x32_bf16 v[54:57], v[176:179], v[192:195], v[54:57]
	v_mfma_f32_16x16x32_bf16 v[50:53], v[184:187], v[192:195], v[50:53]
	v_mfma_f32_16x16x32_bf16 v[38:41], v[176:179], v[200:203], v[38:41]
	v_mfma_f32_16x16x32_bf16 v[34:37], v[184:187], v[200:203], v[34:37]
	v_mfma_f32_16x16x32_bf16 v[22:25], v[176:179], v[208:211], v[22:25]
	v_mfma_f32_16x16x32_bf16 v[18:21], v[184:187], v[208:211], v[18:21]
	v_mfma_f32_16x16x32_bf16 v[6:9], v[176:179], v[216:219], v[6:9]
	v_mfma_f32_16x16x32_bf16 v[2:5], v[184:187], v[216:219], v[2:5]
	v_mfma_f32_16x16x32_bf16 v[54:57], v[180:183], v[196:199], v[54:57]
	v_mfma_f32_16x16x32_bf16 v[50:53], v[188:191], v[196:199], v[50:53]
	v_mfma_f32_16x16x32_bf16 v[38:41], v[180:183], v[204:207], v[38:41]
	v_mfma_f32_16x16x32_bf16 v[34:37], v[188:191], v[204:207], v[34:37]
	v_mfma_f32_16x16x32_bf16 v[22:25], v[180:183], v[212:215], v[22:25]
	v_mfma_f32_16x16x32_bf16 v[18:21], v[188:191], v[212:215], v[18:21]
	v_mfma_f32_16x16x32_bf16 v[6:9], v[180:183], v[224:227], v[6:9]
	v_mfma_f32_16x16x32_bf16 v[2:5], v[188:191], v[224:227], v[2:5]
	s_barrier
	s_add_i32 s42, s42, 2
	s_add_u32 s6, s6, 0x100
	s_addc_u32 s7, s7, 0
	s_add_u32 s40, s40, 0x100
	s_addc_u32 s41, s41, 0
	s_cmp_gt_u32 s42, 29
	s_cbranch_scc0 .LBB0_123
	s_and_b64 vcc, exec, s[12:13]
	s_cbranch_vccz .LBB0_126
	s_barrier
